# MLA: per-tile row-sum update as four interleaved partial sums instead of one 32-deep dependent chain of packed adds padded with s_nop
# speedup vs baseline: 1.0370x; 1.0033x over previous
; DI float ex2(float x) { return __builtin_amdgcn_exp2f(x); }
; DI void phase_mla(const Prm& p, unsigned char* smem_raw, int S, int lgS, int& base) {
;     ...
;       lsum2 *= alpha;
;       const f32x2 mn2 = {mnew, mnew};
; #pragma unroll
;       for (int kk = 0; kk < 4; ++kk)
; #pragma unroll
;         for (int r2 = 0; r2 < 8; ++r2) {
;           f32x2 v = {s[kk][2 * r2], s[kk][2 * r2 + 1]};
;           v = v - mn2;
;           f32x2 pv;
;           pv[0] = ex2(v[0]); pv[1] = ex2(v[1]);
;           lsum2 += pv;
;           s[kk][2 * r2] = pv[0]; s[kk][2 * r2 + 1] = pv[1];
;         }
;     ...
;       if (kt + 1 < nkt) sstore(buf ^ 1);
;       __syncthreads();
.LBB0_2178:
	v_pk_fma_f32 v[64:65], v[176:177], v[178:179], v[82:83] op_sel_hi:[1,0,1]
	s_addk_i32 s66, 0x80
	v_pk_add_f32 v[64:65], v[84:85], v[64:65]
	v_pk_add_f32 v[66:67], v[68:69], v[66:67]
	v_pk_add_f32 v[50:51], v[52:53], v[50:51]
	v_pk_add_f32 v[34:35], v[36:37], v[34:35]
	s_cmp_eq_u32 s72, s4
	v_mov_b32_e32 v159, v0
	s_mov_b32 s5, s4
	v_pk_add_f32 v[64:65], v[86:87], v[64:65]
	v_pk_add_f32 v[66:67], v[70:71], v[66:67]
	v_pk_add_f32 v[50:51], v[54:55], v[50:51]
	v_pk_add_f32 v[34:35], v[38:39], v[34:35]
	s_waitcnt lgkmcnt(0)
	s_barrier
	v_pk_add_f32 v[64:65], v[88:89], v[64:65]
	v_pk_add_f32 v[66:67], v[72:73], v[66:67]
	v_pk_add_f32 v[50:51], v[56:57], v[50:51]
	v_pk_add_f32 v[34:35], v[40:41], v[34:35]
	v_pk_add_f32 v[64:65], v[90:91], v[64:65]
	v_pk_add_f32 v[66:67], v[74:75], v[66:67]
	v_pk_add_f32 v[50:51], v[58:59], v[50:51]
	v_pk_add_f32 v[34:35], v[42:43], v[34:35]
	v_pk_add_f32 v[64:65], v[92:93], v[64:65]
	v_pk_add_f32 v[66:67], v[76:77], v[66:67]
	v_pk_add_f32 v[50:51], v[60:61], v[50:51]
	v_pk_add_f32 v[34:35], v[44:45], v[34:35]
	v_pk_add_f32 v[64:65], v[94:95], v[64:65]
	v_pk_add_f32 v[66:67], v[78:79], v[66:67]
	v_pk_add_f32 v[50:51], v[62:63], v[50:51]
	v_pk_add_f32 v[34:35], v[46:47], v[34:35]
	v_pk_add_f32 v[64:65], v[96:97], v[64:65]
	v_pk_add_f32 v[66:67], v[80:81], v[66:67]
	v_pk_add_f32 v[34:35], v[48:49], v[34:35]
	v_pk_add_f32 v[66:67], v[180:181], v[66:67]
	v_pk_add_f32 v[64:65], v[66:67], v[64:65]
	v_pk_add_f32 v[50:51], v[34:35], v[50:51]
	s_nop 0
	v_pk_add_f32 v[176:177], v[50:51], v[64:65]
	s_cbranch_scc1 .LBB0_2176
